# long-conv MFMA groups: next A fragment also read early, right after the resident-A MFMAs release its register
# speedup vs baseline: 1.0063x; 1.0017x over previous
; #define MFMA(a, b, c) __builtin_amdgcn_mfma_f32_32x32x16_bf16((a), (b), (c), 0, 0, 0)
; __device__ __forceinline__ void toeplitz_item(const Params& p, int layer, int half, int c, bf16* sm, int dry, unsigned* done_ctr) {
;     ...
;       for (int ni = 0; ni < 2; ++ni) {
;         const int nlo = 32 * wn + 64 * ni;
;         actv[ni] = half ? true : !((nlo + 31 - D < 0) || (nlo - D >= 128));
;         const int n = nlo + r;
;         const int src = n - D;
;         const bool valid = half ? ((unsigned)((n & 15) - D) < 16u) : ((unsigned)src < 128u);
;         bblk[ni] = valid ? src : 128;
;       }
;       if (!actv[0] && !actv[1]) continue;
;       const int tb = 16 * (3 - Dl) + 16 + hh - rt;
;       const bf16* ap0 = sW + (aq * 83 + tb - 4 * (2 * wm)) * 8;
;       const bf16* bp0 = sU + bblk[0] * 136 + 8 * hh;
;       const bf16* bp1 = sU + bblk[1] * 136 + 8 * hh;
;       if (actv[0] && actv[1]) {
; #pragma unroll
;         for (int ks = 0; ks < 8; ++ks) {
;           const s8v a0 = *(const s8v*)(ap0 + 16 * ks), a1 = *(const s8v*)(ap0 - 32 + 16 * ks);
;           const s8v b0 = *(const s8v*)(bp0 + 16 * ks), b1 = *(const s8v*)(bp1 + 16 * ks);
;           acc[0][0] = MFMA(a0, b0, acc[0][0]);
;           acc[1][0] = MFMA(a1, b0, acc[1][0]);
;           acc[0][1] = MFMA(a0, b1, acc[0][1]);
;           acc[1][1] = MFMA(a1, b1, acc[1][1]);
;         }
.LBB0_1147:
	s_or_b64 exec, exec, s[2:3]
	v_add_u32_e32 v66, 3, v123
	v_add_u32_e32 v124, s74, v122
	v_cmp_gt_u32_e64 s[2:3], 16, v66
	v_add_u32_e32 v66, 0x1100, v124
	ds_read_b128 v[70:73], v89 offset:35088
	v_cndmask_b32_e64 v66, v228, v66, s[2:3]
	v_add_u32_e32 v125, v90, v66
	ds_read_b128 v[66:69], v89 offset:35024
	ds_read_b128 v[74:77], v125
	v_add_u32_e32 v78, 0x5500, v124
	s_waitcnt lgkmcnt(0)
	v_mfma_f32_32x32x16_bf16 v[50:65], v[70:73], v[74:77], v[50:65]
	s_addk_i32 s74, 0xfbc0
	s_cmpk_eq_i32 s74, 0xe240
	v_mfma_f32_32x32x16_bf16 v[18:33], v[66:69], v[74:77], v[18:33]
	v_cndmask_b32_e64 v74, v228, v78, s[2:3]
	v_add_u32_e32 v134, v90, v74
	ds_read_b128 v[74:77], v134
	ds_read_b128 v[78:81], v89 offset:35120
	ds_read_b128 v[126:129], v125 offset:32
	s_waitcnt lgkmcnt(2)
	v_mfma_f32_32x32x16_bf16 v[34:49], v[70:73], v[74:77], v[34:49]
	v_mfma_f32_32x32x16_bf16 v[2:17], v[66:69], v[74:77], v[2:17]
	ds_read_b128 v[74:77], v89 offset:35056
	s_waitcnt lgkmcnt(1)
	v_mfma_f32_32x32x16_bf16 v[50:65], v[78:81], v[126:129], v[50:65]
	s_waitcnt lgkmcnt(0)
	v_mfma_f32_32x32x16_bf16 v[18:33], v[74:77], v[126:129], v[18:33]
	ds_read_b128 v[126:129], v134 offset:32
	s_waitcnt lgkmcnt(0)
	v_mfma_f32_32x32x16_bf16 v[34:49], v[78:81], v[126:129], v[34:49]
	v_mfma_f32_32x32x16_bf16 v[2:17], v[74:77], v[126:129], v[2:17]
	ds_read_b128 v[130:133], v125 offset:64
	ds_read_b128 v[200:203], v134 offset:64
	ds_read_b128 v[126:129], v89 offset:35152
	ds_read_b128 v[204:207], v125 offset:96
	ds_read_b128 v[208:211], v134 offset:96
	s_waitcnt lgkmcnt(4)
	v_mfma_f32_32x32x16_bf16 v[18:33], v[70:73], v[130:133], v[18:33]
	s_waitcnt lgkmcnt(3)
	v_mfma_f32_32x32x16_bf16 v[2:17], v[70:73], v[200:203], v[2:17]
	ds_read_b128 v[70:73], v89 offset:35184
	s_waitcnt lgkmcnt(3)
	v_mfma_f32_32x32x16_bf16 v[50:65], v[126:129], v[130:133], v[50:65]
	v_mfma_f32_32x32x16_bf16 v[34:49], v[126:129], v[200:203], v[34:49]
	ds_read_b128 v[130:133], v125 offset:128
	ds_read_b128 v[200:203], v134 offset:128
	s_waitcnt lgkmcnt(4)
	v_mfma_f32_32x32x16_bf16 v[18:33], v[78:81], v[204:207], v[18:33]
	s_waitcnt lgkmcnt(3)
	v_mfma_f32_32x32x16_bf16 v[2:17], v[78:81], v[208:211], v[2:17]
	ds_read_b128 v[78:81], v89 offset:35216
	s_waitcnt lgkmcnt(3)
	v_mfma_f32_32x32x16_bf16 v[50:65], v[70:73], v[204:207], v[50:65]
	v_mfma_f32_32x32x16_bf16 v[34:49], v[70:73], v[208:211], v[34:49]
	ds_read_b128 v[204:207], v125 offset:160
	ds_read_b128 v[208:211], v134 offset:160
	s_waitcnt lgkmcnt(4)
	v_mfma_f32_32x32x16_bf16 v[18:33], v[126:129], v[130:133], v[18:33]
	s_waitcnt lgkmcnt(3)
	v_mfma_f32_32x32x16_bf16 v[2:17], v[126:129], v[200:203], v[2:17]
	ds_read_b128 v[126:129], v89 offset:35248
	s_waitcnt lgkmcnt(3)
	v_mfma_f32_32x32x16_bf16 v[50:65], v[78:81], v[130:133], v[50:65]
	v_mfma_f32_32x32x16_bf16 v[34:49], v[78:81], v[200:203], v[34:49]
	ds_read_b128 v[130:133], v125 offset:192
	ds_read_b128 v[200:203], v134 offset:192
	s_waitcnt lgkmcnt(4)
	v_mfma_f32_32x32x16_bf16 v[18:33], v[70:73], v[204:207], v[18:33]
	s_waitcnt lgkmcnt(3)
	v_mfma_f32_32x32x16_bf16 v[2:17], v[70:73], v[208:211], v[2:17]
	ds_read_b128 v[70:73], v89 offset:35280
	s_waitcnt lgkmcnt(3)
	v_mfma_f32_32x32x16_bf16 v[50:65], v[126:129], v[204:207], v[50:65]
	v_mfma_f32_32x32x16_bf16 v[34:49], v[126:129], v[208:211], v[34:49]
	s_waitcnt lgkmcnt(2)
	v_mfma_f32_32x32x16_bf16 v[18:33], v[78:81], v[130:133], v[18:33]
	s_waitcnt lgkmcnt(1)
	v_mfma_f32_32x32x16_bf16 v[2:17], v[78:81], v[200:203], v[2:17]
	s_waitcnt lgkmcnt(0)
	v_mfma_f32_32x32x16_bf16 v[50:65], v[70:73], v[130:133], v[50:65]
	v_mfma_f32_32x32x16_bf16 v[34:49], v[70:73], v[200:203], v[34:49]
	ds_read_b128 v[70:73], v89 offset:35312
	ds_read_b128 v[78:81], v125 offset:224
	v_add_u32_e32 v130, 0x53f0, v124
	s_waitcnt lgkmcnt(0)
	v_mfma_f32_32x32x16_bf16 v[50:65], v[70:73], v[78:81], v[50:65]
	v_mfma_f32_32x32x16_bf16 v[18:33], v[126:129], v[78:81], v[18:33]
	ds_read_b128 v[78:81], v134 offset:224
	s_waitcnt lgkmcnt(0)
	v_mfma_f32_32x32x16_bf16 v[34:49], v[70:73], v[78:81], v[34:49]
	v_add_u32_e32 v70, 2, v123
	v_cmp_gt_u32_e64 s[2:3], 16, v70
	v_add_u32_e32 v70, 0xff0, v124
	s_nop 0
	v_cndmask_b32_e64 v70, v228, v70, s[2:3]
	v_add_u32_e32 v125, v90, v70
	ds_read_b128 v[70:73], v89 offset:34768
	v_mfma_f32_32x32x16_bf16 v[2:17], v[126:129], v[78:81], v[2:17]
	ds_read_b128 v[126:129], v89 offset:34832
	ds_read_b128 v[78:81], v125
	s_waitcnt lgkmcnt(0)
	v_mfma_f32_32x32x16_bf16 v[50:65], v[126:129], v[78:81], v[50:65]
	v_mfma_f32_32x32x16_bf16 v[18:33], v[70:73], v[78:81], v[18:33]
	v_cndmask_b32_e64 v78, v228, v130, s[2:3]
	v_add_u32_e32 v142, v90, v78
	ds_read_b128 v[78:81], v142
	ds_read_b128 v[130:133], v89 offset:34864
	ds_read_b128 v[134:137], v125 offset:32
	s_waitcnt lgkmcnt(2)
	v_mfma_f32_32x32x16_bf16 v[34:49], v[126:129], v[78:81], v[34:49]
	v_mfma_f32_32x32x16_bf16 v[2:17], v[70:73], v[78:81], v[2:17]
	ds_read_b128 v[78:81], v89 offset:34800
	s_waitcnt lgkmcnt(1)
	v_mfma_f32_32x32x16_bf16 v[50:65], v[130:133], v[134:137], v[50:65]
	s_waitcnt lgkmcnt(0)
	v_mfma_f32_32x32x16_bf16 v[18:33], v[78:81], v[134:137], v[18:33]
	ds_read_b128 v[134:137], v142 offset:32
	s_waitcnt lgkmcnt(0)
	v_mfma_f32_32x32x16_bf16 v[34:49], v[130:133], v[134:137], v[34:49]
	v_mfma_f32_32x32x16_bf16 v[2:17], v[78:81], v[134:137], v[2:17]
	ds_read_b128 v[138:141], v125 offset:64
	ds_read_b128 v[200:203], v142 offset:64
	ds_read_b128 v[134:137], v89 offset:34896
	ds_read_b128 v[204:207], v125 offset:96
	ds_read_b128 v[208:211], v142 offset:96
	s_waitcnt lgkmcnt(4)
	v_mfma_f32_32x32x16_bf16 v[18:33], v[126:129], v[138:141], v[18:33]
	s_waitcnt lgkmcnt(3)
; #define MFMA(a, b, c) __builtin_amdgcn_mfma_f32_32x32x16_bf16((a), (b), (c), 0, 0, 0)
; __device__ __forceinline__ void toeplitz_item(const Params& p, int layer, int half, int c, bf16* sm, int dry, unsigned* done_ctr) {
;     ...
;       if (actv[0] && actv[1]) {
; #pragma unroll
;         for (int ks = 0; ks < 8; ++ks) {
;           const s8v a0 = *(const s8v*)(ap0 + 16 * ks), a1 = *(const s8v*)(ap0 - 32 + 16 * ks);
;           const s8v b0 = *(const s8v*)(bp0 + 16 * ks), b1 = *(const s8v*)(bp1 + 16 * ks);
;           acc[0][0] = MFMA(a0, b0, acc[0][0]);
;           acc[1][0] = MFMA(a1, b0, acc[1][0]);
;           acc[0][1] = MFMA(a0, b1, acc[0][1]);
;           acc[1][1] = MFMA(a1, b1, acc[1][1]);
;         }
	v_mfma_f32_32x32x16_bf16 v[2:17], v[126:129], v[200:203], v[2:17]
	ds_read_b128 v[126:129], v89 offset:34928
	s_waitcnt lgkmcnt(3)
	v_mfma_f32_32x32x16_bf16 v[50:65], v[134:137], v[138:141], v[50:65]
	v_mfma_f32_32x32x16_bf16 v[34:49], v[134:137], v[200:203], v[34:49]
	ds_read_b128 v[138:141], v125 offset:128
	ds_read_b128 v[200:203], v142 offset:128
	s_waitcnt lgkmcnt(4)
	v_mfma_f32_32x32x16_bf16 v[18:33], v[130:133], v[204:207], v[18:33]
	s_waitcnt lgkmcnt(3)
	v_mfma_f32_32x32x16_bf16 v[2:17], v[130:133], v[208:211], v[2:17]
	ds_read_b128 v[130:133], v89 offset:34960
	s_waitcnt lgkmcnt(3)
	v_mfma_f32_32x32x16_bf16 v[50:65], v[126:129], v[204:207], v[50:65]
	v_mfma_f32_32x32x16_bf16 v[34:49], v[126:129], v[208:211], v[34:49]
	s_waitcnt lgkmcnt(2)
	v_mfma_f32_32x32x16_bf16 v[18:33], v[134:137], v[138:141], v[18:33]
	s_waitcnt lgkmcnt(1)
	v_mfma_f32_32x32x16_bf16 v[2:17], v[134:137], v[200:203], v[2:17]
	s_waitcnt lgkmcnt(0)
	v_mfma_f32_32x32x16_bf16 v[50:65], v[130:133], v[138:141], v[50:65]
	v_mfma_f32_32x32x16_bf16 v[34:49], v[130:133], v[200:203], v[34:49]
	ds_read_b128 v[134:137], v89 offset:34992
	ds_read_b128 v[138:141], v125 offset:160
	s_waitcnt lgkmcnt(0)
	v_mfma_f32_32x32x16_bf16 v[50:65], v[134:137], v[138:141], v[50:65]
	v_mfma_f32_32x32x16_bf16 v[18:33], v[126:129], v[138:141], v[18:33]
	ds_read_b128 v[138:141], v142 offset:160
	s_waitcnt lgkmcnt(0)
	v_mfma_f32_32x32x16_bf16 v[2:17], v[126:129], v[138:141], v[2:17]
	ds_read_b128 v[126:129], v125 offset:192
	v_mfma_f32_32x32x16_bf16 v[34:49], v[134:137], v[138:141], v[34:49]
	s_waitcnt lgkmcnt(0)
	v_mfma_f32_32x32x16_bf16 v[50:65], v[66:69], v[126:129], v[50:65]
	v_mfma_f32_32x32x16_bf16 v[18:33], v[130:133], v[126:129], v[18:33]
	ds_read_b128 v[126:129], v142 offset:192
	s_waitcnt lgkmcnt(0)
	v_mfma_f32_32x32x16_bf16 v[34:49], v[66:69], v[126:129], v[34:49]
	ds_read_b128 v[66:69], v125 offset:224
	v_mfma_f32_32x32x16_bf16 v[2:17], v[130:133], v[126:129], v[2:17]
	ds_read_b128 v[126:129], v89 offset:34576
	v_add_u32_e32 v130, 0x52e0, v124
	s_waitcnt lgkmcnt(1)
	v_mfma_f32_32x32x16_bf16 v[50:65], v[74:77], v[66:69], v[50:65]
	v_mfma_f32_32x32x16_bf16 v[18:33], v[134:137], v[66:69], v[18:33]
	ds_read_b128 v[66:69], v142 offset:224
	s_waitcnt lgkmcnt(0)
	v_mfma_f32_32x32x16_bf16 v[34:49], v[74:77], v[66:69], v[34:49]
	v_mfma_f32_32x32x16_bf16 v[2:17], v[134:137], v[66:69], v[2:17]
	v_add_u32_e32 v66, 1, v123
	v_cmp_gt_u32_e64 s[2:3], 16, v66
	v_add_u32_e32 v66, 0xee0, v124
	s_nop 0
	v_cndmask_b32_e64 v66, v228, v66, s[2:3]
	v_add_u32_e32 v125, v90, v66
	ds_read_b128 v[66:69], v89 offset:34512
	ds_read_b128 v[74:77], v125
	s_waitcnt lgkmcnt(0)
	v_mfma_f32_32x32x16_bf16 v[50:65], v[126:129], v[74:77], v[50:65]
	v_mfma_f32_32x32x16_bf16 v[18:33], v[66:69], v[74:77], v[18:33]
	v_cndmask_b32_e64 v74, v228, v130, s[2:3]
	v_add_u32_e32 v142, v90, v74
	ds_read_b128 v[74:77], v142
	ds_read_b128 v[130:133], v89 offset:34608
	ds_read_b128 v[134:137], v125 offset:32
	v_cmp_gt_u32_e64 s[2:3], 16, v123
	v_add_u32_e32 v123, -4, v123
	s_waitcnt lgkmcnt(2)
	v_mfma_f32_32x32x16_bf16 v[34:49], v[126:129], v[74:77], v[34:49]
	v_mfma_f32_32x32x16_bf16 v[2:17], v[66:69], v[74:77], v[2:17]
	ds_read_b128 v[74:77], v89 offset:34544
	s_waitcnt lgkmcnt(1)
	v_mfma_f32_32x32x16_bf16 v[50:65], v[130:133], v[134:137], v[50:65]
	s_waitcnt lgkmcnt(0)
	v_mfma_f32_32x32x16_bf16 v[18:33], v[74:77], v[134:137], v[18:33]
	ds_read_b128 v[134:137], v142 offset:32
	s_waitcnt lgkmcnt(0)
	v_mfma_f32_32x32x16_bf16 v[34:49], v[130:133], v[134:137], v[34:49]
	v_mfma_f32_32x32x16_bf16 v[2:17], v[74:77], v[134:137], v[2:17]
	ds_read_b128 v[138:141], v125 offset:64
	ds_read_b128 v[200:203], v142 offset:64
	ds_read_b128 v[134:137], v89 offset:34640
	ds_read_b128 v[204:207], v125 offset:96
	ds_read_b128 v[208:211], v142 offset:96
	s_waitcnt lgkmcnt(4)
	v_mfma_f32_32x32x16_bf16 v[18:33], v[126:129], v[138:141], v[18:33]
	s_waitcnt lgkmcnt(3)
	v_mfma_f32_32x32x16_bf16 v[2:17], v[126:129], v[200:203], v[2:17]
	ds_read_b128 v[126:129], v89 offset:34672
	s_waitcnt lgkmcnt(3)
	v_mfma_f32_32x32x16_bf16 v[50:65], v[134:137], v[138:141], v[50:65]
	v_mfma_f32_32x32x16_bf16 v[34:49], v[134:137], v[200:203], v[34:49]
	ds_read_b128 v[138:141], v125 offset:128
	ds_read_b128 v[200:203], v142 offset:128
	s_waitcnt lgkmcnt(4)
	v_mfma_f32_32x32x16_bf16 v[18:33], v[130:133], v[204:207], v[18:33]
	s_waitcnt lgkmcnt(3)
	v_mfma_f32_32x32x16_bf16 v[2:17], v[130:133], v[208:211], v[2:17]
	ds_read_b128 v[130:133], v89 offset:34704
	s_waitcnt lgkmcnt(3)
	v_mfma_f32_32x32x16_bf16 v[50:65], v[126:129], v[204:207], v[50:65]
	v_mfma_f32_32x32x16_bf16 v[34:49], v[126:129], v[208:211], v[34:49]
	s_waitcnt lgkmcnt(2)
	v_mfma_f32_32x32x16_bf16 v[18:33], v[134:137], v[138:141], v[18:33]
	s_waitcnt lgkmcnt(1)
	v_mfma_f32_32x32x16_bf16 v[2:17], v[134:137], v[200:203], v[2:17]
	s_waitcnt lgkmcnt(0)
	v_mfma_f32_32x32x16_bf16 v[50:65], v[130:133], v[138:141], v[50:65]
	v_mfma_f32_32x32x16_bf16 v[34:49], v[130:133], v[200:203], v[34:49]
	ds_read_b128 v[134:137], v89 offset:34736
	ds_read_b128 v[138:141], v125 offset:160
	s_waitcnt lgkmcnt(0)
; #define MFMA(a, b, c) __builtin_amdgcn_mfma_f32_32x32x16_bf16((a), (b), (c), 0, 0, 0)
; __device__ __forceinline__ void toeplitz_item(const Params& p, int layer, int half, int c, bf16* sm, int dry, unsigned* done_ctr) {
;     ...
;       if (actv[0] && actv[1]) {
; #pragma unroll
;         for (int ks = 0; ks < 8; ++ks) {
;           const s8v a0 = *(const s8v*)(ap0 + 16 * ks), a1 = *(const s8v*)(ap0 - 32 + 16 * ks);
;           const s8v b0 = *(const s8v*)(bp0 + 16 * ks), b1 = *(const s8v*)(bp1 + 16 * ks);
;           acc[0][0] = MFMA(a0, b0, acc[0][0]);
;           acc[1][0] = MFMA(a1, b0, acc[1][0]);
;           acc[0][1] = MFMA(a0, b1, acc[0][1]);
;           acc[1][1] = MFMA(a1, b1, acc[1][1]);
;         }
	v_mfma_f32_32x32x16_bf16 v[50:65], v[134:137], v[138:141], v[50:65]
	v_mfma_f32_32x32x16_bf16 v[18:33], v[126:129], v[138:141], v[18:33]
	ds_read_b128 v[138:141], v142 offset:160
	s_waitcnt lgkmcnt(0)
	v_mfma_f32_32x32x16_bf16 v[2:17], v[126:129], v[138:141], v[2:17]
	ds_read_b128 v[126:129], v125 offset:192
	v_mfma_f32_32x32x16_bf16 v[34:49], v[134:137], v[138:141], v[34:49]
	s_waitcnt lgkmcnt(0)
	v_mfma_f32_32x32x16_bf16 v[50:65], v[70:73], v[126:129], v[50:65]
	v_mfma_f32_32x32x16_bf16 v[18:33], v[130:133], v[126:129], v[18:33]
	ds_read_b128 v[126:129], v142 offset:192
	s_waitcnt lgkmcnt(0)
	v_mfma_f32_32x32x16_bf16 v[34:49], v[70:73], v[126:129], v[34:49]
	ds_read_b128 v[70:73], v125 offset:224
	v_mfma_f32_32x32x16_bf16 v[2:17], v[130:133], v[126:129], v[2:17]
	ds_read_b128 v[126:129], v89 offset:34256
	s_waitcnt lgkmcnt(1)
	v_mfma_f32_32x32x16_bf16 v[50:65], v[78:81], v[70:73], v[50:65]
	v_mfma_f32_32x32x16_bf16 v[18:33], v[134:137], v[70:73], v[18:33]
	ds_read_b128 v[70:73], v142 offset:224
	s_waitcnt lgkmcnt(0)
	v_mfma_f32_32x32x16_bf16 v[34:49], v[78:81], v[70:73], v[34:49]
	v_add_u32_e32 v78, 0xdd0, v124
	v_cndmask_b32_e64 v78, v228, v78, s[2:3]
	v_add_u32_e32 v132, v90, v78
	ds_read_b128 v[78:81], v132
	v_add_u32_e32 v124, 0x51d0, v124
	v_mfma_f32_32x32x16_bf16 v[2:17], v[134:137], v[70:73], v[2:17]
	ds_read_b128 v[70:73], v89 offset:34320
	s_waitcnt lgkmcnt(0)
	v_mfma_f32_32x32x16_bf16 v[50:65], v[70:73], v[78:81], v[50:65]
	v_mfma_f32_32x32x16_bf16 v[18:33], v[126:129], v[78:81], v[18:33]
	v_cndmask_b32_e64 v78, v228, v124, s[2:3]
	v_add_u32_e32 v133, v90, v78
	ds_read_b128 v[78:81], v133
	s_movk_i32 s2, 0xfc00
	s_mov_b32 s3, -1
	v_lshl_add_u64 v[82:83], v[82:83], 0, s[2:3]
	v_lshl_add_u64 v[84:85], v[84:85], 0, s[2:3]
	s_waitcnt lgkmcnt(0)
	v_mfma_f32_32x32x16_bf16 v[34:49], v[70:73], v[78:81], v[34:49]
	v_lshl_add_u64 v[86:87], v[86:87], 0, s[2:3]
	v_mfma_f32_32x32x16_bf16 v[2:17], v[126:129], v[78:81], v[2:17]
	ds_read_b128 v[78:81], v89 offset:34352
	ds_read_b128 v[124:127], v132 offset:32
	ds_read_b128 v[128:131], v89 offset:34288
	s_waitcnt lgkmcnt(1)
	v_mfma_f32_32x32x16_bf16 v[50:65], v[78:81], v[124:127], v[50:65]
	s_waitcnt lgkmcnt(0)
	v_mfma_f32_32x32x16_bf16 v[18:33], v[128:131], v[124:127], v[18:33]
	ds_read_b128 v[124:127], v133 offset:32
	s_waitcnt lgkmcnt(0)
	v_mfma_f32_32x32x16_bf16 v[34:49], v[78:81], v[124:127], v[34:49]
	v_mfma_f32_32x32x16_bf16 v[2:17], v[128:131], v[124:127], v[2:17]
	ds_read_b128 v[128:131], v132 offset:64
	ds_read_b128 v[200:203], v133 offset:64
	ds_read_b128 v[124:127], v89 offset:34384
	ds_read_b128 v[204:207], v132 offset:96
	ds_read_b128 v[208:211], v133 offset:96
	s_waitcnt lgkmcnt(4)
	v_mfma_f32_32x32x16_bf16 v[18:33], v[70:73], v[128:131], v[18:33]
	s_waitcnt lgkmcnt(3)
	v_mfma_f32_32x32x16_bf16 v[2:17], v[70:73], v[200:203], v[2:17]
	ds_read_b128 v[70:73], v89 offset:34416
	s_waitcnt lgkmcnt(3)
	v_mfma_f32_32x32x16_bf16 v[50:65], v[124:127], v[128:131], v[50:65]
	v_mfma_f32_32x32x16_bf16 v[34:49], v[124:127], v[200:203], v[34:49]
	ds_read_b128 v[128:131], v132 offset:128
	ds_read_b128 v[200:203], v133 offset:128
	s_waitcnt lgkmcnt(4)
	v_mfma_f32_32x32x16_bf16 v[18:33], v[78:81], v[204:207], v[18:33]
	s_waitcnt lgkmcnt(3)
	v_mfma_f32_32x32x16_bf16 v[2:17], v[78:81], v[208:211], v[2:17]
	ds_read_b128 v[78:81], v89 offset:34448
	s_waitcnt lgkmcnt(3)
	v_mfma_f32_32x32x16_bf16 v[50:65], v[70:73], v[204:207], v[50:65]
	v_mfma_f32_32x32x16_bf16 v[34:49], v[70:73], v[208:211], v[34:49]
	s_waitcnt lgkmcnt(2)
	v_mfma_f32_32x32x16_bf16 v[18:33], v[124:127], v[128:131], v[18:33]
	s_waitcnt lgkmcnt(1)
	v_mfma_f32_32x32x16_bf16 v[2:17], v[124:127], v[200:203], v[2:17]
	s_waitcnt lgkmcnt(0)
	v_mfma_f32_32x32x16_bf16 v[50:65], v[78:81], v[128:131], v[50:65]
	v_mfma_f32_32x32x16_bf16 v[34:49], v[78:81], v[200:203], v[34:49]
	ds_read_b128 v[124:127], v89 offset:34480
	ds_read_b128 v[128:131], v132 offset:160
	s_waitcnt lgkmcnt(0)
	v_mfma_f32_32x32x16_bf16 v[50:65], v[124:127], v[128:131], v[50:65]
	v_mfma_f32_32x32x16_bf16 v[18:33], v[70:73], v[128:131], v[18:33]
	ds_read_b128 v[128:131], v133 offset:160
	s_waitcnt lgkmcnt(0)
	v_mfma_f32_32x32x16_bf16 v[2:17], v[70:73], v[128:131], v[2:17]
	ds_read_b128 v[70:73], v132 offset:192
	v_mfma_f32_32x32x16_bf16 v[34:49], v[124:127], v[128:131], v[34:49]
	s_waitcnt lgkmcnt(0)
	v_mfma_f32_32x32x16_bf16 v[50:65], v[66:69], v[70:73], v[50:65]
	v_mfma_f32_32x32x16_bf16 v[18:33], v[78:81], v[70:73], v[18:33]
	ds_read_b128 v[70:73], v133 offset:192
	s_waitcnt lgkmcnt(0)
	v_mfma_f32_32x32x16_bf16 v[34:49], v[66:69], v[70:73], v[34:49]
	ds_read_b128 v[66:69], v132 offset:224
	v_mfma_f32_32x32x16_bf16 v[2:17], v[78:81], v[70:73], v[2:17]
	s_waitcnt lgkmcnt(0)
	v_mfma_f32_32x32x16_bf16 v[50:65], v[74:77], v[66:69], v[50:65]
	v_mfma_f32_32x32x16_bf16 v[18:33], v[124:127], v[66:69], v[18:33]
	ds_read_b128 v[66:69], v133 offset:224
	s_waitcnt lgkmcnt(0)
	v_mfma_f32_32x32x16_bf16 v[34:49], v[74:77], v[66:69], v[34:49]
	v_mfma_f32_32x32x16_bf16 v[2:17], v[124:127], v[66:69], v[2:17]
	s_cbranch_scc1 .LBB0_1205

; #define MFMA(a, b, c) __builtin_amdgcn_mfma_f32_32x32x16_bf16((a), (b), (c), 0, 0, 0)
; __device__ __forceinline__ void toeplitz_item(const Params& p, int layer, int half, int c, bf16* sm, int dry, unsigned* done_ctr) {
;     ...
;       if (actv[0] && actv[1]) {
; #pragma unroll
;         for (int ks = 0; ks < 8; ++ks) {
;           const s8v a0 = *(const s8v*)(ap0 + 16 * ks), a1 = *(const s8v*)(ap0 - 32 + 16 * ks);
;           const s8v b0 = *(const s8v*)(bp0 + 16 * ks), b1 = *(const s8v*)(bp1 + 16 * ks);
;           acc[0][0] = MFMA(a0, b0, acc[0][0]);
;           acc[1][0] = MFMA(a1, b0, acc[1][0]);
;           acc[0][1] = MFMA(a0, b1, acc[0][1]);
;           acc[1][1] = MFMA(a1, b1, acc[1][1]);
;         }
.LBB0_1429:
	s_andn2_saveexec_b64 s[94:95], s[20:21]
	s_cbranch_execz .LBB0_1431
	v_add_u32_e32 v14, v106, v14
	s_waitcnt lgkmcnt(0)
	ds_read_b128 v[6:9], v14
	v_add_u32_e32 v15, v106, v15
	s_waitcnt lgkmcnt(0)
	v_mfma_f32_32x32x16_bf16 v[64:79], v[2:5], v[6:9], v[64:79]
	v_mfma_f32_32x32x16_bf16 v[32:47], v[84:87], v[6:9], v[32:47]
	ds_read_b128 v[6:9], v15
	s_waitcnt lgkmcnt(0)
	v_mfma_f32_32x32x16_bf16 v[48:63], v[2:5], v[6:9], v[48:63]
	v_mfma_f32_32x32x16_bf16 v[16:31], v[84:87], v[6:9], v[16:31]
	ds_read_b128 v[6:9], v108 offset:35120
	ds_read_b128 v[10:13], v14 offset:32
	ds_read_b128 v[80:83], v108 offset:35056
	s_waitcnt lgkmcnt(1)
	v_mfma_f32_32x32x16_bf16 v[64:79], v[6:9], v[10:13], v[64:79]
	s_waitcnt lgkmcnt(0)
	v_mfma_f32_32x32x16_bf16 v[32:47], v[80:83], v[10:13], v[32:47]
	ds_read_b128 v[10:13], v15 offset:32
	s_waitcnt lgkmcnt(0)
	v_mfma_f32_32x32x16_bf16 v[48:63], v[6:9], v[10:13], v[48:63]
	v_mfma_f32_32x32x16_bf16 v[16:31], v[80:83], v[10:13], v[16:31]
	ds_read_b128 v[80:83], v14 offset:64
	ds_read_b128 v[200:203], v15 offset:64
	ds_read_b128 v[10:13], v108 offset:35152
	ds_read_b128 v[204:207], v14 offset:96
	ds_read_b128 v[208:211], v15 offset:96
	s_waitcnt lgkmcnt(4)
	v_mfma_f32_32x32x16_bf16 v[32:47], v[2:5], v[80:83], v[32:47]
	s_waitcnt lgkmcnt(3)
	v_mfma_f32_32x32x16_bf16 v[16:31], v[2:5], v[200:203], v[16:31]
	ds_read_b128 v[2:5], v108 offset:35184
	s_waitcnt lgkmcnt(3)
	v_mfma_f32_32x32x16_bf16 v[64:79], v[10:13], v[80:83], v[64:79]
	v_mfma_f32_32x32x16_bf16 v[48:63], v[10:13], v[200:203], v[48:63]
	ds_read_b128 v[80:83], v14 offset:128
	ds_read_b128 v[200:203], v15 offset:128
	s_waitcnt lgkmcnt(4)
	v_mfma_f32_32x32x16_bf16 v[32:47], v[6:9], v[204:207], v[32:47]
	s_waitcnt lgkmcnt(3)
	v_mfma_f32_32x32x16_bf16 v[16:31], v[6:9], v[208:211], v[16:31]
	ds_read_b128 v[6:9], v108 offset:35216
	s_waitcnt lgkmcnt(3)
	v_mfma_f32_32x32x16_bf16 v[64:79], v[2:5], v[204:207], v[64:79]
	v_mfma_f32_32x32x16_bf16 v[48:63], v[2:5], v[208:211], v[48:63]
	ds_read_b128 v[204:207], v14 offset:160
	ds_read_b128 v[208:211], v15 offset:160
	s_waitcnt lgkmcnt(4)
	v_mfma_f32_32x32x16_bf16 v[32:47], v[10:13], v[80:83], v[32:47]
	s_waitcnt lgkmcnt(3)
	v_mfma_f32_32x32x16_bf16 v[16:31], v[10:13], v[200:203], v[16:31]
	ds_read_b128 v[10:13], v108 offset:35248
	s_waitcnt lgkmcnt(3)
	v_mfma_f32_32x32x16_bf16 v[64:79], v[6:9], v[80:83], v[64:79]
	v_mfma_f32_32x32x16_bf16 v[48:63], v[6:9], v[200:203], v[48:63]
	s_waitcnt lgkmcnt(2)
	v_mfma_f32_32x32x16_bf16 v[32:47], v[2:5], v[204:207], v[32:47]
	s_waitcnt lgkmcnt(1)
	v_mfma_f32_32x32x16_bf16 v[16:31], v[2:5], v[208:211], v[16:31]
	s_waitcnt lgkmcnt(0)
	v_mfma_f32_32x32x16_bf16 v[64:79], v[10:13], v[204:207], v[64:79]
	v_mfma_f32_32x32x16_bf16 v[48:63], v[10:13], v[208:211], v[48:63]
	ds_read_b128 v[2:5], v108 offset:35280
	ds_read_b128 v[80:83], v14 offset:192
	s_waitcnt lgkmcnt(0)
	v_mfma_f32_32x32x16_bf16 v[64:79], v[2:5], v[80:83], v[64:79]
	v_mfma_f32_32x32x16_bf16 v[32:47], v[6:9], v[80:83], v[32:47]
	ds_read_b128 v[80:83], v15 offset:192
	s_waitcnt lgkmcnt(0)
	v_mfma_f32_32x32x16_bf16 v[48:63], v[2:5], v[80:83], v[48:63]
	v_mfma_f32_32x32x16_bf16 v[16:31], v[6:9], v[80:83], v[16:31]
	ds_read_b128 v[2:5], v108 offset:35312
	ds_read_b128 v[6:9], v14 offset:224
	s_waitcnt lgkmcnt(0)
	v_mfma_f32_32x32x16_bf16 v[64:79], v[2:5], v[6:9], v[64:79]
	v_mfma_f32_32x32x16_bf16 v[32:47], v[10:13], v[6:9], v[32:47]
	ds_read_b128 v[6:9], v15 offset:224
	s_waitcnt lgkmcnt(0)
	v_mfma_f32_32x32x16_bf16 v[48:63], v[2:5], v[6:9], v[48:63]
	v_mfma_f32_32x32x16_bf16 v[16:31], v[10:13], v[6:9], v[16:31]

; #define MFMA(a, b, c) __builtin_amdgcn_mfma_f32_32x32x16_bf16((a), (b), (c), 0, 0, 0)
; __device__ __forceinline__ void toeplitz_item(const Params& p, int layer, int half, int c, bf16* sm, int dry, unsigned* done_ctr) {
;     ...
;       if (actv[0] && actv[1]) {
; #pragma unroll
;         for (int ks = 0; ks < 8; ++ks) {
;           const s8v a0 = *(const s8v*)(ap0 + 16 * ks), a1 = *(const s8v*)(ap0 - 32 + 16 * ks);
;           const s8v b0 = *(const s8v*)(bp0 + 16 * ks), b1 = *(const s8v*)(bp1 + 16 * ks);
;           acc[0][0] = MFMA(a0, b0, acc[0][0]);
;           acc[1][0] = MFMA(a1, b0, acc[1][0]);
;           acc[0][1] = MFMA(a0, b1, acc[0][1]);
;           acc[1][1] = MFMA(a1, b1, acc[1][1]);
;         }
.LBB0_1439:
	s_andn2_saveexec_b64 s[20:21], s[20:21]
	s_cbranch_execz .LBB0_1441
	v_add_u32_e32 v14, v106, v14
	s_waitcnt lgkmcnt(0)
	ds_read_b128 v[6:9], v14
	v_add_u32_e32 v15, v106, v15
	s_waitcnt lgkmcnt(0)
	v_mfma_f32_32x32x16_bf16 v[64:79], v[2:5], v[6:9], v[64:79]
	v_mfma_f32_32x32x16_bf16 v[32:47], v[84:87], v[6:9], v[32:47]
	ds_read_b128 v[6:9], v15
	s_waitcnt lgkmcnt(0)
	v_mfma_f32_32x32x16_bf16 v[48:63], v[2:5], v[6:9], v[48:63]
	v_mfma_f32_32x32x16_bf16 v[16:31], v[84:87], v[6:9], v[16:31]
	ds_read_b128 v[6:9], v108 offset:34864
	ds_read_b128 v[10:13], v14 offset:32
	ds_read_b128 v[80:83], v108 offset:34800
	s_waitcnt lgkmcnt(1)
	v_mfma_f32_32x32x16_bf16 v[64:79], v[6:9], v[10:13], v[64:79]
	s_waitcnt lgkmcnt(0)
	v_mfma_f32_32x32x16_bf16 v[32:47], v[80:83], v[10:13], v[32:47]
	ds_read_b128 v[10:13], v15 offset:32
	s_waitcnt lgkmcnt(0)
	v_mfma_f32_32x32x16_bf16 v[48:63], v[6:9], v[10:13], v[48:63]
	v_mfma_f32_32x32x16_bf16 v[16:31], v[80:83], v[10:13], v[16:31]
	ds_read_b128 v[80:83], v14 offset:64
	ds_read_b128 v[200:203], v15 offset:64
	ds_read_b128 v[10:13], v108 offset:34896
	ds_read_b128 v[204:207], v14 offset:96
	ds_read_b128 v[208:211], v15 offset:96
	s_waitcnt lgkmcnt(4)
	v_mfma_f32_32x32x16_bf16 v[32:47], v[2:5], v[80:83], v[32:47]
	s_waitcnt lgkmcnt(3)
	v_mfma_f32_32x32x16_bf16 v[16:31], v[2:5], v[200:203], v[16:31]
	ds_read_b128 v[2:5], v108 offset:34928
	s_waitcnt lgkmcnt(3)
	v_mfma_f32_32x32x16_bf16 v[64:79], v[10:13], v[80:83], v[64:79]
	v_mfma_f32_32x32x16_bf16 v[48:63], v[10:13], v[200:203], v[48:63]
	ds_read_b128 v[80:83], v14 offset:128
	ds_read_b128 v[200:203], v15 offset:128
	s_waitcnt lgkmcnt(4)
	v_mfma_f32_32x32x16_bf16 v[32:47], v[6:9], v[204:207], v[32:47]
	s_waitcnt lgkmcnt(3)
	v_mfma_f32_32x32x16_bf16 v[16:31], v[6:9], v[208:211], v[16:31]
	ds_read_b128 v[6:9], v108 offset:34960
	s_waitcnt lgkmcnt(3)
	v_mfma_f32_32x32x16_bf16 v[64:79], v[2:5], v[204:207], v[64:79]
	v_mfma_f32_32x32x16_bf16 v[48:63], v[2:5], v[208:211], v[48:63]
	ds_read_b128 v[204:207], v14 offset:160
	ds_read_b128 v[208:211], v15 offset:160
	s_waitcnt lgkmcnt(4)
	v_mfma_f32_32x32x16_bf16 v[32:47], v[10:13], v[80:83], v[32:47]
	s_waitcnt lgkmcnt(3)
	v_mfma_f32_32x32x16_bf16 v[16:31], v[10:13], v[200:203], v[16:31]
	ds_read_b128 v[10:13], v108 offset:34992
	s_waitcnt lgkmcnt(3)
	v_mfma_f32_32x32x16_bf16 v[64:79], v[6:9], v[80:83], v[64:79]
	v_mfma_f32_32x32x16_bf16 v[48:63], v[6:9], v[200:203], v[48:63]
	s_waitcnt lgkmcnt(2)
	v_mfma_f32_32x32x16_bf16 v[32:47], v[2:5], v[204:207], v[32:47]
	s_waitcnt lgkmcnt(1)
	v_mfma_f32_32x32x16_bf16 v[16:31], v[2:5], v[208:211], v[16:31]
	s_waitcnt lgkmcnt(0)
	v_mfma_f32_32x32x16_bf16 v[64:79], v[10:13], v[204:207], v[64:79]
	v_mfma_f32_32x32x16_bf16 v[48:63], v[10:13], v[208:211], v[48:63]
	ds_read_b128 v[2:5], v108 offset:35024
	ds_read_b128 v[80:83], v14 offset:192
	s_waitcnt lgkmcnt(0)
	v_mfma_f32_32x32x16_bf16 v[64:79], v[2:5], v[80:83], v[64:79]
	v_mfma_f32_32x32x16_bf16 v[32:47], v[6:9], v[80:83], v[32:47]
	ds_read_b128 v[80:83], v15 offset:192
	s_waitcnt lgkmcnt(0)
	v_mfma_f32_32x32x16_bf16 v[48:63], v[2:5], v[80:83], v[48:63]
	v_mfma_f32_32x32x16_bf16 v[16:31], v[6:9], v[80:83], v[16:31]
	ds_read_b128 v[2:5], v108 offset:35056
	ds_read_b128 v[6:9], v14 offset:224
	s_waitcnt lgkmcnt(0)
	v_mfma_f32_32x32x16_bf16 v[64:79], v[2:5], v[6:9], v[64:79]
	v_mfma_f32_32x32x16_bf16 v[32:47], v[10:13], v[6:9], v[32:47]
	ds_read_b128 v[6:9], v15 offset:224
	s_waitcnt lgkmcnt(0)
	v_mfma_f32_32x32x16_bf16 v[48:63], v[2:5], v[6:9], v[48:63]
	v_mfma_f32_32x32x16_bf16 v[16:31], v[10:13], v[6:9], v[16:31]

; #define MFMA(a, b, c) __builtin_amdgcn_mfma_f32_32x32x16_bf16((a), (b), (c), 0, 0, 0)
; __device__ __forceinline__ void toeplitz_item(const Params& p, int layer, int half, int c, bf16* sm, int dry, unsigned* done_ctr) {
;     ...
;       if (actv[0] && actv[1]) {
; #pragma unroll
;         for (int ks = 0; ks < 8; ++ks) {
;           const s8v a0 = *(const s8v*)(ap0 + 16 * ks), a1 = *(const s8v*)(ap0 - 32 + 16 * ks);
;           const s8v b0 = *(const s8v*)(bp0 + 16 * ks), b1 = *(const s8v*)(bp1 + 16 * ks);
;           acc[0][0] = MFMA(a0, b0, acc[0][0]);
;           acc[1][0] = MFMA(a1, b0, acc[1][0]);
;           acc[0][1] = MFMA(a0, b1, acc[0][1]);
;           acc[1][1] = MFMA(a1, b1, acc[1][1]);
;         }
.LBB0_1449:
	s_andn2_saveexec_b64 s[20:21], s[20:21]
	s_cbranch_execz .LBB0_1451
	v_add_u32_e32 v14, v106, v14
	s_waitcnt lgkmcnt(0)
	ds_read_b128 v[6:9], v14
	v_add_u32_e32 v15, v106, v15
	s_waitcnt lgkmcnt(0)
	v_mfma_f32_32x32x16_bf16 v[64:79], v[2:5], v[6:9], v[64:79]
	v_mfma_f32_32x32x16_bf16 v[32:47], v[84:87], v[6:9], v[32:47]
	ds_read_b128 v[6:9], v15
	s_waitcnt lgkmcnt(0)
	v_mfma_f32_32x32x16_bf16 v[48:63], v[2:5], v[6:9], v[48:63]
	v_mfma_f32_32x32x16_bf16 v[16:31], v[84:87], v[6:9], v[16:31]
	ds_read_b128 v[6:9], v108 offset:34608
	ds_read_b128 v[10:13], v14 offset:32
	ds_read_b128 v[80:83], v108 offset:34544
	s_waitcnt lgkmcnt(1)
	v_mfma_f32_32x32x16_bf16 v[64:79], v[6:9], v[10:13], v[64:79]
	s_waitcnt lgkmcnt(0)
	v_mfma_f32_32x32x16_bf16 v[32:47], v[80:83], v[10:13], v[32:47]
	ds_read_b128 v[10:13], v15 offset:32
	s_waitcnt lgkmcnt(0)
	v_mfma_f32_32x32x16_bf16 v[48:63], v[6:9], v[10:13], v[48:63]
	v_mfma_f32_32x32x16_bf16 v[16:31], v[80:83], v[10:13], v[16:31]
	ds_read_b128 v[80:83], v14 offset:64
	ds_read_b128 v[200:203], v15 offset:64
	ds_read_b128 v[10:13], v108 offset:34640
	ds_read_b128 v[204:207], v14 offset:96
	ds_read_b128 v[208:211], v15 offset:96
	s_waitcnt lgkmcnt(4)
	v_mfma_f32_32x32x16_bf16 v[32:47], v[2:5], v[80:83], v[32:47]
	s_waitcnt lgkmcnt(3)
	v_mfma_f32_32x32x16_bf16 v[16:31], v[2:5], v[200:203], v[16:31]
	ds_read_b128 v[2:5], v108 offset:34672
	s_waitcnt lgkmcnt(3)
	v_mfma_f32_32x32x16_bf16 v[64:79], v[10:13], v[80:83], v[64:79]
	v_mfma_f32_32x32x16_bf16 v[48:63], v[10:13], v[200:203], v[48:63]
	ds_read_b128 v[80:83], v14 offset:128
	ds_read_b128 v[200:203], v15 offset:128
	s_waitcnt lgkmcnt(4)
	v_mfma_f32_32x32x16_bf16 v[32:47], v[6:9], v[204:207], v[32:47]
	s_waitcnt lgkmcnt(3)
	v_mfma_f32_32x32x16_bf16 v[16:31], v[6:9], v[208:211], v[16:31]
	ds_read_b128 v[6:9], v108 offset:34704
	s_waitcnt lgkmcnt(3)
	v_mfma_f32_32x32x16_bf16 v[64:79], v[2:5], v[204:207], v[64:79]
	v_mfma_f32_32x32x16_bf16 v[48:63], v[2:5], v[208:211], v[48:63]
	ds_read_b128 v[204:207], v14 offset:160
	ds_read_b128 v[208:211], v15 offset:160
	s_waitcnt lgkmcnt(4)
	v_mfma_f32_32x32x16_bf16 v[32:47], v[10:13], v[80:83], v[32:47]
	s_waitcnt lgkmcnt(3)
	v_mfma_f32_32x32x16_bf16 v[16:31], v[10:13], v[200:203], v[16:31]
	ds_read_b128 v[10:13], v108 offset:34736
	s_waitcnt lgkmcnt(3)
	v_mfma_f32_32x32x16_bf16 v[64:79], v[6:9], v[80:83], v[64:79]
	v_mfma_f32_32x32x16_bf16 v[48:63], v[6:9], v[200:203], v[48:63]
	s_waitcnt lgkmcnt(2)
	v_mfma_f32_32x32x16_bf16 v[32:47], v[2:5], v[204:207], v[32:47]
	s_waitcnt lgkmcnt(1)
	v_mfma_f32_32x32x16_bf16 v[16:31], v[2:5], v[208:211], v[16:31]
	s_waitcnt lgkmcnt(0)
	v_mfma_f32_32x32x16_bf16 v[64:79], v[10:13], v[204:207], v[64:79]
	v_mfma_f32_32x32x16_bf16 v[48:63], v[10:13], v[208:211], v[48:63]
	ds_read_b128 v[2:5], v108 offset:34768
	ds_read_b128 v[80:83], v14 offset:192
	s_waitcnt lgkmcnt(0)
	v_mfma_f32_32x32x16_bf16 v[64:79], v[2:5], v[80:83], v[64:79]
	v_mfma_f32_32x32x16_bf16 v[32:47], v[6:9], v[80:83], v[32:47]
	ds_read_b128 v[80:83], v15 offset:192
	s_waitcnt lgkmcnt(0)
	v_mfma_f32_32x32x16_bf16 v[48:63], v[2:5], v[80:83], v[48:63]
	v_mfma_f32_32x32x16_bf16 v[16:31], v[6:9], v[80:83], v[16:31]
	ds_read_b128 v[2:5], v108 offset:34800
	ds_read_b128 v[6:9], v14 offset:224
	s_waitcnt lgkmcnt(0)
	v_mfma_f32_32x32x16_bf16 v[64:79], v[2:5], v[6:9], v[64:79]
	v_mfma_f32_32x32x16_bf16 v[32:47], v[10:13], v[6:9], v[32:47]
	ds_read_b128 v[6:9], v15 offset:224
	s_waitcnt lgkmcnt(0)
	v_mfma_f32_32x32x16_bf16 v[48:63], v[2:5], v[6:9], v[48:63]
	v_mfma_f32_32x32x16_bf16 v[16:31], v[10:13], v[6:9], v[16:31]

; #define MFMA(a, b, c) __builtin_amdgcn_mfma_f32_32x32x16_bf16((a), (b), (c), 0, 0, 0)
; __device__ __forceinline__ void toeplitz_item(const Params& p, int layer, int half, int c, bf16* sm, int dry, unsigned* done_ctr) {
;     ...
;       if (actv[0] && actv[1]) {
; #pragma unroll
;         for (int ks = 0; ks < 8; ++ks) {
;           const s8v a0 = *(const s8v*)(ap0 + 16 * ks), a1 = *(const s8v*)(ap0 - 32 + 16 * ks);
;           const s8v b0 = *(const s8v*)(bp0 + 16 * ks), b1 = *(const s8v*)(bp1 + 16 * ks);
;           acc[0][0] = MFMA(a0, b0, acc[0][0]);
;           acc[1][0] = MFMA(a1, b0, acc[1][0]);
;           acc[0][1] = MFMA(a0, b1, acc[0][1]);
;           acc[1][1] = MFMA(a1, b1, acc[1][1]);
;         }
.LBB0_1459:
	s_andn2_saveexec_b64 s[20:21], s[20:21]
	s_cbranch_execz .LBB0_1369
	v_add_u32_e32 v0, v106, v0
	s_waitcnt lgkmcnt(0)
	ds_read_b128 v[6:9], v0
	v_add_u32_e32 v14, v106, v14
	s_waitcnt lgkmcnt(0)
	v_mfma_f32_32x32x16_bf16 v[64:79], v[2:5], v[6:9], v[64:79]
	v_mfma_f32_32x32x16_bf16 v[32:47], v[84:87], v[6:9], v[32:47]
	ds_read_b128 v[6:9], v14
	s_waitcnt lgkmcnt(0)
	v_mfma_f32_32x32x16_bf16 v[48:63], v[2:5], v[6:9], v[48:63]
	v_mfma_f32_32x32x16_bf16 v[16:31], v[84:87], v[6:9], v[16:31]
	ds_read_b128 v[6:9], v108 offset:34352
	ds_read_b128 v[10:13], v0 offset:32
	ds_read_b128 v[80:83], v108 offset:34288
	s_waitcnt lgkmcnt(1)
	v_mfma_f32_32x32x16_bf16 v[64:79], v[6:9], v[10:13], v[64:79]
	s_waitcnt lgkmcnt(0)
	v_mfma_f32_32x32x16_bf16 v[32:47], v[80:83], v[10:13], v[32:47]
	ds_read_b128 v[10:13], v14 offset:32
	s_waitcnt lgkmcnt(0)
	v_mfma_f32_32x32x16_bf16 v[48:63], v[6:9], v[10:13], v[48:63]
	v_mfma_f32_32x32x16_bf16 v[16:31], v[80:83], v[10:13], v[16:31]
	ds_read_b128 v[80:83], v0 offset:64
	ds_read_b128 v[200:203], v14 offset:64
	ds_read_b128 v[10:13], v108 offset:34384
	ds_read_b128 v[204:207], v0 offset:96
	ds_read_b128 v[208:211], v14 offset:96
	s_waitcnt lgkmcnt(4)
	v_mfma_f32_32x32x16_bf16 v[32:47], v[2:5], v[80:83], v[32:47]
	s_waitcnt lgkmcnt(3)
	v_mfma_f32_32x32x16_bf16 v[16:31], v[2:5], v[200:203], v[16:31]
	ds_read_b128 v[2:5], v108 offset:34416
	s_waitcnt lgkmcnt(3)
	v_mfma_f32_32x32x16_bf16 v[64:79], v[10:13], v[80:83], v[64:79]
	v_mfma_f32_32x32x16_bf16 v[48:63], v[10:13], v[200:203], v[48:63]
	ds_read_b128 v[80:83], v0 offset:128
	ds_read_b128 v[200:203], v14 offset:128
	s_waitcnt lgkmcnt(4)
	v_mfma_f32_32x32x16_bf16 v[32:47], v[6:9], v[204:207], v[32:47]
	s_waitcnt lgkmcnt(3)
	v_mfma_f32_32x32x16_bf16 v[16:31], v[6:9], v[208:211], v[16:31]
	ds_read_b128 v[6:9], v108 offset:34448
	s_waitcnt lgkmcnt(3)
	v_mfma_f32_32x32x16_bf16 v[64:79], v[2:5], v[204:207], v[64:79]
	v_mfma_f32_32x32x16_bf16 v[48:63], v[2:5], v[208:211], v[48:63]
	ds_read_b128 v[204:207], v0 offset:160
	ds_read_b128 v[208:211], v14 offset:160
	s_waitcnt lgkmcnt(4)
	v_mfma_f32_32x32x16_bf16 v[32:47], v[10:13], v[80:83], v[32:47]
	s_waitcnt lgkmcnt(3)
	v_mfma_f32_32x32x16_bf16 v[16:31], v[10:13], v[200:203], v[16:31]
	ds_read_b128 v[10:13], v108 offset:34480
	s_waitcnt lgkmcnt(3)
	v_mfma_f32_32x32x16_bf16 v[64:79], v[6:9], v[80:83], v[64:79]
	v_mfma_f32_32x32x16_bf16 v[48:63], v[6:9], v[200:203], v[48:63]
	s_waitcnt lgkmcnt(2)
	v_mfma_f32_32x32x16_bf16 v[32:47], v[2:5], v[204:207], v[32:47]
	s_waitcnt lgkmcnt(1)
	v_mfma_f32_32x32x16_bf16 v[16:31], v[2:5], v[208:211], v[16:31]
	s_waitcnt lgkmcnt(0)
	v_mfma_f32_32x32x16_bf16 v[64:79], v[10:13], v[204:207], v[64:79]
	v_mfma_f32_32x32x16_bf16 v[48:63], v[10:13], v[208:211], v[48:63]
	ds_read_b128 v[2:5], v108 offset:34512
	ds_read_b128 v[80:83], v0 offset:192
	s_waitcnt lgkmcnt(0)
	v_mfma_f32_32x32x16_bf16 v[64:79], v[2:5], v[80:83], v[64:79]
	v_mfma_f32_32x32x16_bf16 v[32:47], v[6:9], v[80:83], v[32:47]
	ds_read_b128 v[80:83], v14 offset:192
	s_waitcnt lgkmcnt(0)
	v_mfma_f32_32x32x16_bf16 v[48:63], v[2:5], v[80:83], v[48:63]
	v_mfma_f32_32x32x16_bf16 v[16:31], v[6:9], v[80:83], v[16:31]
	ds_read_b128 v[2:5], v108 offset:34544
	ds_read_b128 v[6:9], v0 offset:224
	s_waitcnt lgkmcnt(0)
	v_mfma_f32_32x32x16_bf16 v[64:79], v[2:5], v[6:9], v[64:79]
	v_mfma_f32_32x32x16_bf16 v[32:47], v[10:13], v[6:9], v[32:47]
	ds_read_b128 v[6:9], v14 offset:224
	s_waitcnt lgkmcnt(0)
	v_mfma_f32_32x32x16_bf16 v[48:63], v[2:5], v[6:9], v[48:63]
	v_mfma_f32_32x32x16_bf16 v[16:31], v[10:13], v[6:9], v[16:31]
	s_branch .LBB0_1369
